# grid barrier: every block issues its invalidate right behind the arrival atomic (waits only for the atomic), no invalidate on the release path
# speedup vs baseline: 1.0196x; 1.0030x over previous
.LBB0_925:
	s_mov_b64 s[4:5], exec
	v_mbcnt_lo_u32_b32 v0, s4, 0
	v_mbcnt_hi_u32_b32 v0, s5, v0
	v_cmp_eq_u32_e32 vcc, 0, v0
	s_and_saveexec_b64 s[2:3], vcc
	s_cbranch_execz .LBB0_927
	s_bcnt1_i32_b64 s4, s[4:5]
	v_mov_b32_e32 v4, s4
	v_readlane_b32 s4, v244, 2
	v_readlane_b32 s5, v244, 3
	s_nop 4
	global_atomic_add v4, v1, v4, s[4:5] sc0
	buffer_inv sc1
.LBB0_927:
	s_or_b64 exec, exec, s[2:3]
	v_cvt_f32_u32_e32 v5, v3
	s_waitcnt vmcnt(1)
	v_readfirstlane_b32 s2, v4
	v_sub_u32_e32 v4, 0, v3
	v_rcp_iflag_f32_e32 v5, v5
	v_add_u32_e32 v6, s2, v0
	v_mul_f32_e32 v5, 0x4f7ffffe, v5
	v_cvt_u32_f32_e32 v5, v5
	v_mul_lo_u32 v0, v4, v5
	v_mul_hi_u32 v0, v5, v0
	v_add_u32_e32 v0, v5, v0
	v_mul_hi_u32 v0, v6, v0
	v_mul_lo_u32 v4, v0, v3
	v_sub_u32_e32 v4, v6, v4
	v_add_u32_e32 v5, 1, v0
	v_cmp_ge_u32_e32 vcc, v4, v3
	s_nop 1
	v_cndmask_b32_e32 v0, v0, v5, vcc
	v_sub_u32_e32 v5, v4, v3
	v_cndmask_b32_e32 v4, v4, v5, vcc
	v_add_u32_e32 v5, 1, v0
	v_cmp_ge_u32_e32 vcc, v4, v3
	v_add_u32_e32 v4, 1, v6
	s_nop 0
	v_cndmask_b32_e32 v0, v0, v5, vcc
	v_mul_lo_u32 v5, v3, v0
	v_add_u32_e32 v3, v5, v3
	v_cmp_ne_u32_e32 vcc, v4, v3
	s_and_saveexec_b64 s[2:3], vcc
	s_xor_b64 s[2:3], exec, s[2:3]
	s_cbranch_execz .LBB0_941
	v_readlane_b32 s4, v244, 4
	v_readlane_b32 s5, v244, 5
	s_waitcnt lgkmcnt(0)
	s_nop 3
	global_load_dword v2, v1, s[4:5] sc1
	s_waitcnt vmcnt(0)
	v_cmp_eq_u32_e32 vcc, v2, v0
	s_and_saveexec_b64 s[4:5], vcc
	s_cbranch_execz .LBB0_940
	s_mov_b32 s8, 1
	s_mov_b64 s[6:7], 0
	s_branch .LBB0_931
